# weight conversion: FFN-up transpose copy issues its 16 loads per iteration together (was 8 serialized 2-load round trips); plus merge+gates epilogues, global_ ops, RG-LRU wait placement
# speedup vs baseline: 1.0092x; 1.0092x over previous
; template <bool FFN_PERM = false>
; __device__ __forceinline__ void transpose_item(const float* W, int ldw, int K, bf16_t* WT, int nblk, int item, LAS float* scr, int lane) {
;     const int kb = item / nblk, nb = item % nblk, k0 = 64 * kb, n0 = 32 * nb;
;     const int d0 = FFN_PERM ? ((n0 < DFF) ? ((n0 >> 7) * 256 + (n0 & 127)) : ((((n0 - DFF) >> 7) * 256) + 128 + ((n0 - DFF) & 127))) : n0;
; #pragma unroll 8
;     for (int i = 0; i < 32; ++i) { const int kk = 2 * i + (lane >> 5); scr[kk * 33 + (lane & 31)] = W[(size_t)(k0 + kk) * ldw + n0 + (lane & 31)]; }
;     asm volatile("s_waitcnt lgkmcnt(0)" ::: "memory");
.LBB0_43:
	s_lshl_b32 s18, s9, 1
	s_lshl_b32 s17, s8, 1
	v_or_b32_e32 v51, s18, v2
	v_or_b32_e32 v3, s17, v1
	v_add_u32_e32 v58, s6, v51
	v_add_u32_e32 v52, s7, v3
	v_mad_u64_u32 v[58:59], s[20:21], v58, s22, v[50:51]
	v_mad_u64_u32 v[52:53], s[20:21], v52, s22, v[50:51]
	v_mov_b32_e32 v59, v0
	v_lshl_add_u64 v[58:59], v[58:59], 2, s[4:5]
	v_mov_b32_e32 v53, v0
	v_lshl_add_u64 v[52:53], v[52:53], 2, s[4:5]
	global_load_dword v60, v[58:59], off
	global_load_dword v61, v[52:53], off
	v_mad_u32_u24 v76, v51, s63, v4
	v_mad_u32_u24 v77, v3, s63, v4
	s_add_i32 s19, s18, 4
	v_or_b32_e32 v51, s19, v2
	s_add_i32 s19, s17, 4
	v_or_b32_e32 v3, s19, v1
	v_add_u32_e32 v58, s6, v51
	v_add_u32_e32 v52, s7, v3
	v_mad_u64_u32 v[58:59], s[20:21], v58, s22, v[50:51]
	v_mad_u64_u32 v[52:53], s[20:21], v52, s22, v[50:51]
	v_mov_b32_e32 v59, v0
	v_lshl_add_u64 v[58:59], v[58:59], 2, s[4:5]
	v_mov_b32_e32 v53, v0
	v_lshl_add_u64 v[52:53], v[52:53], 2, s[4:5]
	global_load_dword v62, v[58:59], off
	global_load_dword v63, v[52:53], off
	v_mad_u32_u24 v78, v51, s63, v4
	v_mad_u32_u24 v79, v3, s63, v4
	s_add_i32 s19, s18, 8
	v_or_b32_e32 v51, s19, v2
	s_add_i32 s19, s17, 8
	v_or_b32_e32 v3, s19, v1
	v_add_u32_e32 v58, s6, v51
	v_add_u32_e32 v52, s7, v3
	v_mad_u64_u32 v[58:59], s[20:21], v58, s22, v[50:51]
	v_mad_u64_u32 v[52:53], s[20:21], v52, s22, v[50:51]
	v_mov_b32_e32 v59, v0
	v_lshl_add_u64 v[58:59], v[58:59], 2, s[4:5]
	v_mov_b32_e32 v53, v0
	v_lshl_add_u64 v[52:53], v[52:53], 2, s[4:5]
	global_load_dword v64, v[58:59], off
	global_load_dword v65, v[52:53], off
	v_mad_u32_u24 v80, v51, s63, v4
	v_mad_u32_u24 v81, v3, s63, v4
	s_add_i32 s19, s18, 12
	v_or_b32_e32 v51, s19, v2
	s_add_i32 s19, s17, 12
	v_or_b32_e32 v3, s19, v1
	v_add_u32_e32 v58, s6, v51
	v_add_u32_e32 v52, s7, v3
	v_mad_u64_u32 v[58:59], s[20:21], v58, s22, v[50:51]
	v_mad_u64_u32 v[52:53], s[20:21], v52, s22, v[50:51]
	v_mov_b32_e32 v59, v0
	v_lshl_add_u64 v[58:59], v[58:59], 2, s[4:5]
	v_mov_b32_e32 v53, v0
	v_lshl_add_u64 v[52:53], v[52:53], 2, s[4:5]
	global_load_dword v66, v[58:59], off
	global_load_dword v67, v[52:53], off
	v_mad_u32_u24 v82, v51, s63, v4
	v_mad_u32_u24 v83, v3, s63, v4
	s_add_i32 s19, s18, 16
	v_or_b32_e32 v51, s19, v2
	s_add_i32 s19, s17, 16
	v_or_b32_e32 v3, s19, v1
	v_add_u32_e32 v58, s6, v51
	v_add_u32_e32 v52, s7, v3
	v_mad_u64_u32 v[58:59], s[20:21], v58, s22, v[50:51]
	v_mad_u64_u32 v[52:53], s[20:21], v52, s22, v[50:51]
	v_mov_b32_e32 v59, v0
	v_lshl_add_u64 v[58:59], v[58:59], 2, s[4:5]
	v_mov_b32_e32 v53, v0
	v_lshl_add_u64 v[52:53], v[52:53], 2, s[4:5]
	global_load_dword v68, v[58:59], off
	global_load_dword v69, v[52:53], off
	v_mad_u32_u24 v84, v51, s63, v4
	v_mad_u32_u24 v85, v3, s63, v4
	s_add_i32 s19, s18, 20
	v_or_b32_e32 v51, s19, v2
	s_add_i32 s19, s17, 20
	v_or_b32_e32 v3, s19, v1
	v_add_u32_e32 v58, s6, v51
	v_add_u32_e32 v52, s7, v3
	v_mad_u64_u32 v[58:59], s[20:21], v58, s22, v[50:51]
	v_mad_u64_u32 v[52:53], s[20:21], v52, s22, v[50:51]
	v_mov_b32_e32 v59, v0
	v_lshl_add_u64 v[58:59], v[58:59], 2, s[4:5]
	v_mov_b32_e32 v53, v0
	v_lshl_add_u64 v[52:53], v[52:53], 2, s[4:5]
	global_load_dword v70, v[58:59], off
	global_load_dword v71, v[52:53], off
	v_mad_u32_u24 v86, v51, s63, v4
	v_mad_u32_u24 v87, v3, s63, v4
	s_add_i32 s19, s18, 24
	v_or_b32_e32 v51, s19, v2
	s_add_i32 s19, s17, 24
	v_or_b32_e32 v3, s19, v1
	v_add_u32_e32 v58, s6, v51
	v_add_u32_e32 v52, s7, v3
	v_mad_u64_u32 v[58:59], s[20:21], v58, s22, v[50:51]
	v_mad_u64_u32 v[52:53], s[20:21], v52, s22, v[50:51]
	v_mov_b32_e32 v59, v0
	v_lshl_add_u64 v[58:59], v[58:59], 2, s[4:5]
	v_mov_b32_e32 v53, v0
	v_lshl_add_u64 v[52:53], v[52:53], 2, s[4:5]
	global_load_dword v72, v[58:59], off
	global_load_dword v73, v[52:53], off
	v_mad_u32_u24 v88, v51, s63, v4
	v_mad_u32_u24 v89, v3, s63, v4
	s_add_i32 s19, s18, 28
	v_or_b32_e32 v51, s19, v2
	s_add_i32 s19, s17, 28
	v_or_b32_e32 v3, s19, v1
	v_add_u32_e32 v58, s6, v51
	v_add_u32_e32 v52, s7, v3
	v_mad_u64_u32 v[58:59], s[20:21], v58, s22, v[50:51]
	v_mad_u64_u32 v[52:53], s[20:21], v52, s22, v[50:51]
	v_mov_b32_e32 v59, v0
	v_lshl_add_u64 v[58:59], v[58:59], 2, s[4:5]
	v_mov_b32_e32 v53, v0
	v_lshl_add_u64 v[52:53], v[52:53], 2, s[4:5]
	global_load_dword v74, v[58:59], off
	global_load_dword v75, v[52:53], off
	v_mad_u32_u24 v90, v51, s63, v4
	v_mad_u32_u24 v91, v3, s63, v4
	s_add_i32 s9, s9, 16
	s_add_i32 s8, s8, 16
	s_add_i32 s16, s16, -16
	s_cmp_lg_u32 s16, 0
	s_waitcnt vmcnt(0)
	ds_write_b32 v76, v60
	ds_write_b32 v77, v61
	ds_write_b32 v78, v62
	ds_write_b32 v79, v63
	ds_write_b32 v80, v64
	ds_write_b32 v81, v65
	ds_write_b32 v82, v66
	ds_write_b32 v83, v67
	ds_write_b32 v84, v68
	ds_write_b32 v85, v69
	ds_write_b32 v86, v70
	ds_write_b32 v87, v71
	ds_write_b32 v88, v72
	ds_write_b32 v89, v73
	ds_write_b32 v90, v74
	ds_write_b32 v91, v75
	s_cbranch_scc1 .LBB0_43
; #define LAS __attribute__((address_space(3)))
; __device__ __forceinline__ unsigned pk2(float lo, float hi) { return f2bf(lo) | (f2bf(hi) << 16); }
; template <bool FFN_PERM = false>
; __device__ __forceinline__ void transpose_item(const float* W, int ldw, int K, bf16_t* WT, int nblk, int item, LAS float* scr, int lane) {
;     ...
;     const int c = lane & 7;
; #pragma unroll
;     for (int j = 0; j < 4; ++j) { const int n = (lane >> 3) + 8 * j; const LAS float* s = scr + (8 * c) * 33 + n;
;         u32x4 o; o.x = pk2(s[0 * 33], s[1 * 33]); o.y = pk2(s[2 * 33], s[3 * 33]); o.z = pk2(s[4 * 33], s[5 * 33]); o.w = pk2(s[6 * 33], s[7 * 33]);
;         *(u32x4*)(WT + (size_t)(d0 + n) * K + k0 + 8 * c) = o; }
;     asm volatile("s_waitcnt lgkmcnt(0)" ::: "memory");
	s_waitcnt lgkmcnt(0)
	ds_read_b32 v3, v54
	ds_read_b32 v50, v54 offset:132
	ds_read_b32 v51, v54 offset:264
	ds_read_b32 v52, v54 offset:396
	ds_read_b32 v53, v54 offset:528
	ds_read_b32 v60, v54 offset:660
	ds_read_b32 v61, v54 offset:792
	ds_read_b32 v62, v54 offset:924
	s_waitcnt lgkmcnt(0)
	v_bfe_u32 v63, v3, 16, 1
	v_add3_u32 v3, v3, v63, s60
	v_bfe_u32 v63, v50, 16, 1
	v_lshrrev_b32_e32 v3, 16, v3
	v_add3_u32 v50, v50, v63, s60
	v_and_or_b32 v50, v50, s61, v3
	v_bfe_u32 v3, v51, 16, 1
	v_add3_u32 v3, v51, v3, s60
	v_bfe_u32 v51, v52, 16, 1
	v_lshrrev_b32_e32 v3, 16, v3
	v_add3_u32 v51, v52, v51, s60
	v_and_or_b32 v51, v51, s61, v3
	v_bfe_u32 v3, v53, 16, 1
	v_add3_u32 v3, v53, v3, s60
	v_bfe_u32 v52, v60, 16, 1
	v_lshrrev_b32_e32 v3, 16, v3
	v_add3_u32 v52, v60, v52, s60
	v_and_or_b32 v52, v52, s61, v3
	v_bfe_u32 v3, v61, 16, 1
	s_lshl_b32 s96, s6, 1
	v_add3_u32 v3, v61, v3, s60
	v_bfe_u32 v53, v62, 16, 1
	v_add_u32_e32 v60, s3, v7
	v_mov_b32_e32 v61, v0
	v_lshl_add_u64 v[58:59], v[10:11], 0, s[96:97]
	v_lshrrev_b32_e32 v3, 16, v3
	v_add3_u32 v53, v62, v53, s60
	v_lshlrev_b64 v[60:61], 11, v[60:61]
	v_and_or_b32 v53, v53, s61, v3
	v_lshl_add_u64 v[60:61], v[58:59], 0, v[60:61]
	global_store_dwordx4 v[60:61], v[50:53], off
	ds_read_b32 v3, v54 offset:32
	ds_read_b32 v50, v54 offset:164
	ds_read_b32 v51, v54 offset:296
	ds_read_b32 v52, v54 offset:428
	ds_read_b32 v53, v54 offset:560
	ds_read_b32 v60, v54 offset:692
	ds_read_b32 v61, v54 offset:824
	ds_read_b32 v62, v54 offset:956
	s_waitcnt lgkmcnt(0)
	v_bfe_u32 v63, v3, 16, 1
	v_add3_u32 v3, v3, v63, s60
	v_bfe_u32 v63, v50, 16, 1
	v_lshrrev_b32_e32 v3, 16, v3
	v_add3_u32 v50, v50, v63, s60
	v_and_or_b32 v50, v50, s61, v3
	v_bfe_u32 v3, v51, 16, 1
	v_add3_u32 v3, v51, v3, s60
	v_bfe_u32 v51, v52, 16, 1
	v_lshrrev_b32_e32 v3, 16, v3
	v_add3_u32 v51, v52, v51, s60
	v_and_or_b32 v51, v51, s61, v3
	v_bfe_u32 v3, v53, 16, 1
	v_add3_u32 v3, v53, v3, s60
	v_bfe_u32 v52, v60, 16, 1
	v_lshrrev_b32_e32 v3, 16, v3
	v_add3_u32 v52, v60, v52, s60
	v_and_or_b32 v52, v52, s61, v3
	v_bfe_u32 v3, v61, 16, 1
	v_add3_u32 v3, v61, v3, s60
	v_bfe_u32 v53, v62, 16, 1
	v_add_u32_e32 v60, s3, v55
	v_mov_b32_e32 v61, v0
	v_lshrrev_b32_e32 v3, 16, v3
	v_add3_u32 v53, v62, v53, s60
	v_lshlrev_b64 v[60:61], 11, v[60:61]
	v_and_or_b32 v53, v53, s61, v3
	v_lshl_add_u64 v[60:61], v[58:59], 0, v[60:61]
	global_store_dwordx4 v[60:61], v[50:53], off
	ds_read_b32 v3, v54 offset:64
	ds_read_b32 v50, v54 offset:196
	ds_read_b32 v51, v54 offset:328
	ds_read_b32 v52, v54 offset:460
	ds_read_b32 v53, v54 offset:592
	ds_read_b32 v60, v54 offset:724
	ds_read_b32 v61, v54 offset:856
	ds_read_b32 v62, v54 offset:988
	s_waitcnt lgkmcnt(0)
	v_bfe_u32 v63, v3, 16, 1
	v_add3_u32 v3, v3, v63, s60
	v_bfe_u32 v63, v50, 16, 1
	v_lshrrev_b32_e32 v3, 16, v3
	v_add3_u32 v50, v50, v63, s60
	v_and_or_b32 v50, v50, s61, v3
	v_bfe_u32 v3, v51, 16, 1
	v_add3_u32 v3, v51, v3, s60
	v_bfe_u32 v51, v52, 16, 1
	v_lshrrev_b32_e32 v3, 16, v3
	v_add3_u32 v51, v52, v51, s60
	v_and_or_b32 v51, v51, s61, v3
	v_bfe_u32 v3, v53, 16, 1
	v_add3_u32 v3, v53, v3, s60
	v_bfe_u32 v52, v60, 16, 1
	v_lshrrev_b32_e32 v3, 16, v3
	v_add3_u32 v52, v60, v52, s60
	v_and_or_b32 v52, v52, s61, v3
	v_bfe_u32 v3, v61, 16, 1
	v_add3_u32 v3, v61, v3, s60
	v_bfe_u32 v53, v62, 16, 1
	v_add_u32_e32 v60, s3, v56
	v_mov_b32_e32 v61, v0
	v_lshrrev_b32_e32 v3, 16, v3
	v_add3_u32 v53, v62, v53, s60
	v_lshlrev_b64 v[60:61], 11, v[60:61]
	v_and_or_b32 v53, v53, s61, v3
	v_lshl_add_u64 v[60:61], v[58:59], 0, v[60:61]
	global_store_dwordx4 v[60:61], v[50:53], off
	ds_read_b32 v3, v54 offset:96
	ds_read_b32 v50, v54 offset:228
	ds_read_b32 v51, v54 offset:360
	ds_read_b32 v52, v54 offset:492
	ds_read_b32 v53, v54 offset:624
	ds_read_b32 v60, v54 offset:756
	ds_read_b32 v61, v54 offset:888
	ds_read_b32 v62, v54 offset:1020
	s_waitcnt lgkmcnt(0)
	v_bfe_u32 v63, v3, 16, 1
	v_add3_u32 v3, v3, v63, s60
	v_bfe_u32 v63, v50, 16, 1
	v_lshrrev_b32_e32 v3, 16, v3
	v_add3_u32 v50, v50, v63, s60
	v_and_or_b32 v50, v50, s61, v3
	v_bfe_u32 v3, v51, 16, 1
	v_add3_u32 v3, v51, v3, s60
	v_bfe_u32 v51, v52, 16, 1
	v_lshrrev_b32_e32 v3, 16, v3
	v_add3_u32 v51, v52, v51, s60
	v_and_or_b32 v51, v51, s61, v3
	v_bfe_u32 v3, v53, 16, 1
	v_add3_u32 v3, v53, v3, s60
	v_bfe_u32 v52, v60, 16, 1
	v_lshrrev_b32_e32 v3, 16, v3
	v_add3_u32 v52, v60, v52, s60
	v_and_or_b32 v52, v52, s61, v3
	v_bfe_u32 v3, v61, 16, 1
	v_add3_u32 v3, v61, v3, s60
	v_bfe_u32 v53, v62, 16, 1
	v_add_u32_e32 v60, s3, v57
	v_mov_b32_e32 v61, v0
	v_lshrrev_b32_e32 v3, 16, v3
	v_add3_u32 v53, v62, v53, s60
	v_lshlrev_b64 v[60:61], 11, v[60:61]
	v_and_or_b32 v53, v53, s61, v3
	v_lshl_add_u64 v[58:59], v[58:59], 0, v[60:61]
	global_store_dwordx4 v[58:59], v[50:53], off
	s_waitcnt lgkmcnt(0)
